# v27: FoX fast path - QK^T MFMAs of the next tile interleaved with row-max/rescale VALU of the current tile (doc lever 8)
# speedup vs baseline: 1.0026x; 1.0011x over previous
.LBB0_387:
	s_add_i32 s4, s20, -5
	s_cmp_lt_u32 s4, s18
	s_cselect_b64 s[16:17], -1, 0
	s_cmp_ge_u32 s4, s18
	s_cbranch_scc1 .LBB0_390
	s_add_i32 s4, s23, 3
	s_cmp_gt_i32 s4, s21
	s_cbranch_scc1 .LBB0_390
	s_add_i32 s4, s23, 4
	s_cmp_gt_i32 s4, s21
	s_cbranch_scc1 .Lfx1_slow
	s_add_i32 s4, s22, 0x80
	s_cmp_le_i32 s4, s31
	s_cbranch_scc0 .Lfx1_slow
	ds_read_b128 v[172:175], v244 offset:864
	ds_read_b128 v[168:171], v244 offset:832
	ds_read_b128 v[164:167], v244 offset:800
	ds_read_b128 v[160:163], v244 offset:768
	ds_read_b128 v[188:191], v244 offset:992
	ds_read_b128 v[184:187], v244 offset:960
	ds_read_b128 v[180:183], v244 offset:928
	ds_read_b128 v[176:179], v244 offset:896
	v_add_u32_e32 v68, v247, v243
	s_waitcnt lgkmcnt(7)
	v_sub_f32_e32 v175, v159, v175
	v_sub_f32_e32 v174, v158, v174
	v_sub_f32_e32 v173, v157, v173
	v_sub_f32_e32 v172, v156, v172
	s_waitcnt lgkmcnt(6)
	v_sub_f32_e32 v171, v155, v171
	v_sub_f32_e32 v170, v154, v170
	v_sub_f32_e32 v169, v153, v169
	v_sub_f32_e32 v168, v152, v168
	s_waitcnt lgkmcnt(5)
	v_sub_f32_e32 v167, v151, v167
	v_sub_f32_e32 v166, v150, v166
	v_sub_f32_e32 v165, v149, v165
	v_sub_f32_e32 v164, v148, v164
	s_waitcnt lgkmcnt(4)
	v_sub_f32_e32 v163, v147, v163
	v_sub_f32_e32 v162, v146, v162
	v_sub_f32_e32 v161, v145, v161
	v_sub_f32_e32 v160, v144, v160
	s_waitcnt lgkmcnt(3)
	v_sub_f32_e32 v191, v159, v191
	v_sub_f32_e32 v190, v158, v190
	v_sub_f32_e32 v189, v157, v189
	v_sub_f32_e32 v188, v156, v188
	s_waitcnt lgkmcnt(2)
	v_sub_f32_e32 v187, v155, v187
	v_sub_f32_e32 v186, v154, v186
	v_sub_f32_e32 v185, v153, v185
	v_sub_f32_e32 v184, v152, v184
	s_waitcnt lgkmcnt(1)
	v_sub_f32_e32 v183, v151, v183
	v_sub_f32_e32 v182, v150, v182
	v_sub_f32_e32 v181, v149, v181
	v_sub_f32_e32 v180, v148, v180
	s_waitcnt lgkmcnt(0)
	v_sub_f32_e32 v179, v147, v179
	v_sub_f32_e32 v178, v146, v178
	v_sub_f32_e32 v177, v145, v177
	v_sub_f32_e32 v176, v144, v176
	ds_read_b128 v[84:87], v68 offset:9216
	ds_read_b128 v[72:75], v68 offset:13824
	ds_read_b128 v[76:79], v68 offset:9248
	ds_read_b128 v[80:83], v68 offset:13856
	v_max_f32_e32 v64, v1, v1
	v_max_f32_e32 v65, v0, v0
	v_max_f32_e32 v64, v65, v64
	v_max3_f32 v64, v64, v2, v3
	v_max3_f32 v64, v64, v4, v5
	v_max3_f32 v64, v64, v6, v7
	s_waitcnt lgkmcnt(3)
	v_mfma_f32_32x32x16_bf16 v[160:175], v[84:87], v[192:195], v[160:175]
	ds_read_b128 v[84:87], v68 offset:9280
	v_max3_f32 v64, v64, v8, v9
	v_max3_f32 v64, v64, v10, v11
	v_max3_f32 v64, v64, v12, v13
	v_max3_f32 v64, v64, v14, v15
	v_max3_f32 v64, v64, v16, v17
	v_max3_f32 v64, v64, v18, v19
	s_waitcnt lgkmcnt(3)
	v_mfma_f32_32x32x16_bf16 v[176:191], v[72:75], v[192:195], v[176:191]
	ds_read_b128 v[72:75], v68 offset:13888
	v_max3_f32 v64, v64, v20, v21
	v_max3_f32 v64, v64, v22, v23
	v_max3_f32 v64, v64, v24, v25
	v_max3_f32 v64, v64, v26, v27
	v_max3_f32 v64, v64, v28, v29
	v_max3_f32 v64, v64, v30, v31
	s_waitcnt lgkmcnt(3)
	v_mfma_f32_32x32x16_bf16 v[160:175], v[76:79], v[196:199], v[160:175]
	ds_read_b128 v[76:79], v68 offset:9312
	v_mov_b32_e32 v65, v64
	v_mov_b32_e32 v66, v64
	s_nop 1
	v_permlane32_swap_b32_e32 v65, v66
	v_cndmask_b32_e64 v65, v65, v66, s[38:39]
	v_max3_f32 v96, v97, v64, v65
	s_waitcnt lgkmcnt(3)
	v_mfma_f32_32x32x16_bf16 v[176:191], v[80:83], v[196:199], v[176:191]
	ds_read_b128 v[80:83], v68 offset:13920
	v_cmp_neq_f32_e32 vcc, s2, v96
	s_nop 1
	v_cndmask_b32_e32 v65, 0, v96, vcc
	v_sub_f32_e32 v64, v97, v65
	v_exp_f32_e32 v64, v64
	s_nop 0
	s_waitcnt lgkmcnt(3)
	v_mfma_f32_32x32x16_bf16 v[160:175], v[84:87], v[200:203], v[160:175]
	v_pk_mul_f32 v[46:47], v[46:47], v[64:65] op_sel_hi:[1,0]
	v_pk_mul_f32 v[44:45], v[44:45], v[64:65] op_sel_hi:[1,0]
	v_pk_mul_f32 v[42:43], v[42:43], v[64:65] op_sel_hi:[1,0]
	v_pk_mul_f32 v[40:41], v[40:41], v[64:65] op_sel_hi:[1,0]
	v_pk_mul_f32 v[38:39], v[38:39], v[64:65] op_sel_hi:[1,0]
	v_pk_mul_f32 v[36:37], v[36:37], v[64:65] op_sel_hi:[1,0]
	s_waitcnt lgkmcnt(2)
	v_mfma_f32_32x32x16_bf16 v[176:191], v[72:75], v[200:203], v[176:191]
	v_pk_mul_f32 v[34:35], v[34:35], v[64:65] op_sel_hi:[1,0]
	v_pk_mul_f32 v[32:33], v[32:33], v[64:65] op_sel_hi:[1,0]
	v_pk_mul_f32 v[62:63], v[62:63], v[64:65] op_sel_hi:[1,0]
	v_pk_mul_f32 v[60:61], v[60:61], v[64:65] op_sel_hi:[1,0]
	v_pk_mul_f32 v[58:59], v[58:59], v[64:65] op_sel_hi:[1,0]
	s_waitcnt lgkmcnt(1)
	v_mfma_f32_32x32x16_bf16 v[160:175], v[76:79], v[204:207], v[160:175]
	v_pk_mul_f32 v[56:57], v[56:57], v[64:65] op_sel_hi:[1,0]
	v_pk_mul_f32 v[54:55], v[54:55], v[64:65] op_sel_hi:[1,0]
	v_pk_mul_f32 v[52:53], v[52:53], v[64:65] op_sel_hi:[1,0]
	v_pk_mul_f32 v[50:51], v[50:51], v[64:65] op_sel_hi:[1,0]
	v_pk_mul_f32 v[48:49], v[48:49], v[64:65] op_sel_hi:[1,0]
	s_waitcnt lgkmcnt(0)
	v_mfma_f32_32x32x16_bf16 v[176:191], v[80:83], v[204:207], v[176:191]
	s_branch .LBB0_397
.Lfx1_slow:
	ds_read_b128 v[172:175], v244 offset:864
	ds_read_b128 v[168:171], v244 offset:832
	ds_read_b128 v[164:167], v244 offset:800
	ds_read_b128 v[160:163], v244 offset:768
	ds_read_b128 v[188:191], v244 offset:992
	ds_read_b128 v[184:187], v244 offset:960
	ds_read_b128 v[180:183], v244 offset:928
	ds_read_b128 v[176:179], v244 offset:896
	v_add_u32_e32 v68, v247, v243
	s_waitcnt lgkmcnt(7)
	v_sub_f32_e32 v175, v159, v175
	v_sub_f32_e32 v174, v158, v174
	v_sub_f32_e32 v173, v157, v173
	v_sub_f32_e32 v172, v156, v172
	s_waitcnt lgkmcnt(6)
	v_sub_f32_e32 v171, v155, v171
	v_sub_f32_e32 v170, v154, v170
	v_sub_f32_e32 v169, v153, v169
	v_sub_f32_e32 v168, v152, v168
	s_waitcnt lgkmcnt(5)
	v_sub_f32_e32 v167, v151, v167
	v_sub_f32_e32 v166, v150, v166
	v_sub_f32_e32 v165, v149, v165
	v_sub_f32_e32 v164, v148, v164
	s_waitcnt lgkmcnt(4)
	v_sub_f32_e32 v163, v147, v163
	v_sub_f32_e32 v162, v146, v162
	v_sub_f32_e32 v161, v145, v161
	v_sub_f32_e32 v160, v144, v160
	s_waitcnt lgkmcnt(3)
	v_sub_f32_e32 v191, v159, v191
	v_sub_f32_e32 v190, v158, v190
	v_sub_f32_e32 v189, v157, v189
	v_sub_f32_e32 v188, v156, v188
	s_waitcnt lgkmcnt(2)
	v_sub_f32_e32 v187, v155, v187
	v_sub_f32_e32 v186, v154, v186
	v_sub_f32_e32 v185, v153, v185
	v_sub_f32_e32 v184, v152, v184
	s_waitcnt lgkmcnt(1)
	v_sub_f32_e32 v183, v151, v183
	v_sub_f32_e32 v182, v150, v182
	v_sub_f32_e32 v181, v149, v181
	v_sub_f32_e32 v180, v148, v180
	s_waitcnt lgkmcnt(0)
	v_sub_f32_e32 v179, v147, v179
	v_sub_f32_e32 v178, v146, v178
	v_sub_f32_e32 v177, v145, v177
	v_sub_f32_e32 v176, v144, v176
	ds_read_b128 v[64:67], v68 offset:9216
	ds_read_b128 v[72:75], v68 offset:13824
	ds_read_b128 v[76:79], v68 offset:9248
	ds_read_b128 v[80:83], v68 offset:13856
	s_waitcnt lgkmcnt(3)
	v_mfma_f32_32x32x16_bf16 v[160:175], v[64:67], v[192:195], v[160:175]
	ds_read_b128 v[64:67], v68 offset:9280
	s_waitcnt lgkmcnt(3)
	v_mfma_f32_32x32x16_bf16 v[176:191], v[72:75], v[192:195], v[176:191]
	ds_read_b128 v[72:75], v68 offset:13888
	s_waitcnt lgkmcnt(3)
	v_mfma_f32_32x32x16_bf16 v[160:175], v[76:79], v[196:199], v[160:175]
	ds_read_b128 v[76:79], v68 offset:9312
	s_waitcnt lgkmcnt(3)
	v_mfma_f32_32x32x16_bf16 v[176:191], v[80:83], v[196:199], v[176:191]
	ds_read_b128 v[80:83], v68 offset:13920
	s_waitcnt lgkmcnt(3)
	v_mfma_f32_32x32x16_bf16 v[160:175], v[64:67], v[200:203], v[160:175]
	s_waitcnt lgkmcnt(2)
	v_mfma_f32_32x32x16_bf16 v[176:191], v[72:75], v[200:203], v[176:191]
	s_waitcnt lgkmcnt(1)
	v_mfma_f32_32x32x16_bf16 v[160:175], v[76:79], v[204:207], v[160:175]
	s_waitcnt lgkmcnt(0)
	v_mfma_f32_32x32x16_bf16 v[176:191], v[80:83], v[204:207], v[176:191]

.LBB0_408:
	s_add_i32 s4, s23, 2
	s_cmp_gt_i32 s4, s21
	s_cbranch_scc1 .LBB0_410
	s_add_i32 s4, s23, 3
	s_cmp_gt_i32 s4, s21
	s_cbranch_scc1 .Lfx2_slow
	s_add_i32 s4, s22, 64
	s_cmp_le_i32 s4, s31
	s_cbranch_scc0 .Lfx2_slow
	ds_read_b128 v[12:15], v244 offset:608
	ds_read_b128 v[8:11], v244 offset:576
	ds_read_b128 v[4:7], v244 offset:544
	ds_read_b128 v[0:3], v244 offset:512
	ds_read_b128 v[28:31], v244 offset:736
	ds_read_b128 v[24:27], v244 offset:704
	ds_read_b128 v[20:23], v244 offset:672
	ds_read_b128 v[16:19], v244 offset:640
	v_add_u32_e32 v68, v247, v243
	s_waitcnt lgkmcnt(7)
	v_sub_f32_e32 v15, v159, v15
	v_sub_f32_e32 v14, v158, v14
	v_sub_f32_e32 v13, v157, v13
	v_sub_f32_e32 v12, v156, v12
	s_waitcnt lgkmcnt(6)
	v_sub_f32_e32 v11, v155, v11
	v_sub_f32_e32 v10, v154, v10
	v_sub_f32_e32 v9, v153, v9
	v_sub_f32_e32 v8, v152, v8
	s_waitcnt lgkmcnt(5)
	v_sub_f32_e32 v7, v151, v7
	v_sub_f32_e32 v6, v150, v6
	v_sub_f32_e32 v5, v149, v5
	v_sub_f32_e32 v4, v148, v4
	s_waitcnt lgkmcnt(4)
	v_sub_f32_e32 v3, v147, v3
	v_sub_f32_e32 v2, v146, v2
	v_sub_f32_e32 v1, v145, v1
	v_sub_f32_e32 v0, v144, v0
	s_waitcnt lgkmcnt(3)
	v_sub_f32_e32 v31, v159, v31
	v_sub_f32_e32 v30, v158, v30
	v_sub_f32_e32 v29, v157, v29
	v_sub_f32_e32 v28, v156, v28
	s_waitcnt lgkmcnt(2)
	v_sub_f32_e32 v27, v155, v27
	v_sub_f32_e32 v26, v154, v26
	v_sub_f32_e32 v25, v153, v25
	v_sub_f32_e32 v24, v152, v24
	s_waitcnt lgkmcnt(1)
	v_sub_f32_e32 v23, v151, v23
	v_sub_f32_e32 v22, v150, v22
	v_sub_f32_e32 v21, v149, v21
	v_sub_f32_e32 v20, v148, v20
	s_waitcnt lgkmcnt(0)
	v_sub_f32_e32 v19, v147, v19
	v_sub_f32_e32 v18, v146, v18
	v_sub_f32_e32 v17, v145, v17
	v_sub_f32_e32 v16, v144, v16
	ds_read_b128 v[64:67], v68
	ds_read_b128 v[136:139], v68 offset:4608
	ds_read_b128 v[140:143], v68 offset:32
	v_max_f32_e32 v97, v161, v161
	v_max_f32_e32 v98, v160, v160
	v_max_f32_e32 v97, v98, v97
	v_max3_f32 v97, v97, v162, v163
	v_max3_f32 v97, v97, v164, v165
	v_max3_f32 v97, v97, v166, v167
	s_waitcnt lgkmcnt(2)
	v_mfma_f32_32x32x16_bf16 v[0:15], v[64:67], v[192:195], v[0:15]
	ds_read_b128 v[64:67], v68 offset:4640
	v_max3_f32 v97, v97, v168, v169
	v_max3_f32 v97, v97, v170, v171
	v_max3_f32 v97, v97, v172, v173
	v_max3_f32 v97, v97, v174, v175
	v_max3_f32 v97, v97, v176, v177
	v_max3_f32 v97, v97, v178, v179
	s_waitcnt lgkmcnt(2)
	v_mfma_f32_32x32x16_bf16 v[16:31], v[136:139], v[192:195], v[16:31]
	ds_read_b128 v[136:139], v68 offset:64
	v_max3_f32 v97, v97, v180, v181
	v_max3_f32 v97, v97, v182, v183
	v_max3_f32 v97, v97, v184, v185
	v_max3_f32 v97, v97, v186, v187
	v_max3_f32 v97, v97, v188, v189
	v_max3_f32 v97, v97, v190, v191
	s_waitcnt lgkmcnt(2)
	v_mfma_f32_32x32x16_bf16 v[0:15], v[140:143], v[196:199], v[0:15]
	ds_read_b128 v[140:143], v68 offset:4672
	v_mov_b32_e32 v98, v97
	v_mov_b32_e32 v99, v97
	s_nop 1
	v_permlane32_swap_b32_e32 v98, v99
	v_cndmask_b32_e64 v98, v98, v99, s[38:39]
	v_max3_f32 v97, v96, v97, v98
	s_waitcnt lgkmcnt(2)
	v_mfma_f32_32x32x16_bf16 v[16:31], v[64:67], v[196:199], v[16:31]
	ds_read_b128 v[64:67], v68 offset:96
	v_cmp_neq_f32_e32 vcc, s2, v97
	s_nop 1
	v_cndmask_b32_e32 v98, 0, v97, vcc
	v_sub_f32_e32 v96, v96, v98
	v_exp_f32_e32 v96, v96
	s_nop 0
	s_waitcnt lgkmcnt(2)
	v_mfma_f32_32x32x16_bf16 v[0:15], v[136:139], v[200:203], v[0:15]
	ds_read_b128 v[136:139], v68 offset:4704
	v_pk_mul_f32 v[46:47], v[46:47], v[96:97] op_sel_hi:[1,0]
	v_pk_mul_f32 v[44:45], v[44:45], v[96:97] op_sel_hi:[1,0]
	v_pk_mul_f32 v[42:43], v[42:43], v[96:97] op_sel_hi:[1,0]
	v_pk_mul_f32 v[40:41], v[40:41], v[96:97] op_sel_hi:[1,0]
	v_pk_mul_f32 v[38:39], v[38:39], v[96:97] op_sel_hi:[1,0]
	v_pk_mul_f32 v[36:37], v[36:37], v[96:97] op_sel_hi:[1,0]
	s_waitcnt lgkmcnt(2)
	v_mfma_f32_32x32x16_bf16 v[16:31], v[140:143], v[200:203], v[16:31]
	v_pk_mul_f32 v[34:35], v[34:35], v[96:97] op_sel_hi:[1,0]
	v_pk_mul_f32 v[32:33], v[32:33], v[96:97] op_sel_hi:[1,0]
	v_pk_mul_f32 v[62:63], v[62:63], v[96:97] op_sel_hi:[1,0]
	v_pk_mul_f32 v[60:61], v[60:61], v[96:97] op_sel_hi:[1,0]
	v_pk_mul_f32 v[58:59], v[58:59], v[96:97] op_sel_hi:[1,0]
	s_waitcnt lgkmcnt(1)
	v_mfma_f32_32x32x16_bf16 v[0:15], v[64:67], v[204:207], v[0:15]
	v_pk_mul_f32 v[56:57], v[56:57], v[96:97] op_sel_hi:[1,0]
	v_pk_mul_f32 v[54:55], v[54:55], v[96:97] op_sel_hi:[1,0]
	v_pk_mul_f32 v[52:53], v[52:53], v[96:97] op_sel_hi:[1,0]
	v_pk_mul_f32 v[50:51], v[50:51], v[96:97] op_sel_hi:[1,0]
	v_pk_mul_f32 v[48:49], v[48:49], v[96:97] op_sel_hi:[1,0]
	s_waitcnt lgkmcnt(0)
	v_mfma_f32_32x32x16_bf16 v[16:31], v[136:139], v[204:207], v[16:31]
	s_branch .LBB0_417
.Lfx2_slow:
	ds_read_b128 v[12:15], v244 offset:608
	ds_read_b128 v[8:11], v244 offset:576
	ds_read_b128 v[4:7], v244 offset:544
	ds_read_b128 v[0:3], v244 offset:512
	ds_read_b128 v[28:31], v244 offset:736
	ds_read_b128 v[24:27], v244 offset:704
	ds_read_b128 v[20:23], v244 offset:672
	ds_read_b128 v[16:19], v244 offset:640
	v_add_u32_e32 v97, v247, v243
	s_waitcnt lgkmcnt(7)
	v_sub_f32_e32 v15, v159, v15
	v_sub_f32_e32 v14, v158, v14
	v_sub_f32_e32 v13, v157, v13
	v_sub_f32_e32 v12, v156, v12
	s_waitcnt lgkmcnt(6)
	v_sub_f32_e32 v11, v155, v11
	v_sub_f32_e32 v10, v154, v10
	v_sub_f32_e32 v9, v153, v9
	v_sub_f32_e32 v8, v152, v8
	s_waitcnt lgkmcnt(5)
	v_sub_f32_e32 v7, v151, v7
	v_sub_f32_e32 v6, v150, v6
	v_sub_f32_e32 v5, v149, v5
	v_sub_f32_e32 v4, v148, v4
	s_waitcnt lgkmcnt(4)
	v_sub_f32_e32 v3, v147, v3
	v_sub_f32_e32 v2, v146, v2
	v_sub_f32_e32 v1, v145, v1
	v_sub_f32_e32 v0, v144, v0
	s_waitcnt lgkmcnt(3)
	v_sub_f32_e32 v31, v159, v31
	v_sub_f32_e32 v30, v158, v30
	v_sub_f32_e32 v29, v157, v29
	v_sub_f32_e32 v28, v156, v28
	s_waitcnt lgkmcnt(2)
	v_sub_f32_e32 v27, v155, v27
	v_sub_f32_e32 v26, v154, v26
	v_sub_f32_e32 v25, v153, v25
	v_sub_f32_e32 v24, v152, v24
	s_waitcnt lgkmcnt(1)
	v_sub_f32_e32 v23, v151, v23
	v_sub_f32_e32 v22, v150, v22
	v_sub_f32_e32 v21, v149, v21
	v_sub_f32_e32 v20, v148, v20
	s_waitcnt lgkmcnt(0)
	v_sub_f32_e32 v19, v147, v19
	v_sub_f32_e32 v18, v146, v18
	v_sub_f32_e32 v17, v145, v17
	v_sub_f32_e32 v16, v144, v16
	ds_read_b128 v[98:101], v97
	ds_read_b128 v[136:139], v97 offset:4608
	ds_read_b128 v[140:143], v97 offset:32
	s_waitcnt lgkmcnt(2)
	v_mfma_f32_32x32x16_bf16 v[0:15], v[98:101], v[192:195], v[0:15]
	ds_read_b128 v[98:101], v97 offset:4640
	s_waitcnt lgkmcnt(2)
	v_mfma_f32_32x32x16_bf16 v[16:31], v[136:139], v[192:195], v[16:31]
	ds_read_b128 v[136:139], v97 offset:64
	s_waitcnt lgkmcnt(2)
	v_mfma_f32_32x32x16_bf16 v[0:15], v[140:143], v[196:199], v[0:15]
	ds_read_b128 v[140:143], v97 offset:4672
	s_waitcnt lgkmcnt(2)
	v_mfma_f32_32x32x16_bf16 v[16:31], v[98:101], v[196:199], v[16:31]
	ds_read_b128 v[98:101], v97 offset:96
	s_waitcnt lgkmcnt(2)
	v_mfma_f32_32x32x16_bf16 v[0:15], v[136:139], v[200:203], v[0:15]
	ds_read_b128 v[136:139], v97 offset:4704
	s_waitcnt lgkmcnt(2)
	v_mfma_f32_32x32x16_bf16 v[16:31], v[140:143], v[200:203], v[16:31]
	s_waitcnt lgkmcnt(1)
	v_mfma_f32_32x32x16_bf16 v[0:15], v[98:101], v[204:207], v[0:15]
	s_waitcnt lgkmcnt(0)
	v_mfma_f32_32x32x16_bf16 v[16:31], v[136:139], v[204:207], v[16:31]

.LBB0_427:
	s_add_i32 s4, s23, 1
	s_cmp_gt_i32 s4, s21
	s_cbranch_scc1 .LBB0_429
	s_add_i32 s4, s23, 2
	s_cmp_gt_i32 s4, s21
	s_cbranch_scc1 .Lfx3_slow
	s_cmp_le_i32 s22, s31
	s_cbranch_scc0 .Lfx3_slow
	ds_read_b128 v[172:175], v244 offset:352
	ds_read_b128 v[168:171], v244 offset:320
	ds_read_b128 v[164:167], v244 offset:288
	ds_read_b128 v[160:163], v244 offset:256
	ds_read_b128 v[188:191], v244 offset:480
	ds_read_b128 v[184:187], v244 offset:448
	ds_read_b128 v[180:183], v244 offset:416
	ds_read_b128 v[176:179], v244 offset:384
	v_add_u32_e32 v96, v247, v243
	s_waitcnt lgkmcnt(7)
	v_sub_f32_e32 v175, v159, v175
	v_sub_f32_e32 v174, v158, v174
	v_sub_f32_e32 v173, v157, v173
	v_sub_f32_e32 v172, v156, v172
	s_waitcnt lgkmcnt(6)
	v_sub_f32_e32 v171, v155, v171
	v_sub_f32_e32 v170, v154, v170
	v_sub_f32_e32 v169, v153, v169
	v_sub_f32_e32 v168, v152, v168
	s_waitcnt lgkmcnt(5)
	v_sub_f32_e32 v167, v151, v167
	v_sub_f32_e32 v166, v150, v166
	v_sub_f32_e32 v165, v149, v165
	v_sub_f32_e32 v164, v148, v164
	s_waitcnt lgkmcnt(4)
	v_sub_f32_e32 v163, v147, v163
	v_sub_f32_e32 v162, v146, v162
	v_sub_f32_e32 v161, v145, v161
	v_sub_f32_e32 v160, v144, v160
	s_waitcnt lgkmcnt(3)
	v_sub_f32_e32 v191, v159, v191
	v_sub_f32_e32 v190, v158, v190
	v_sub_f32_e32 v189, v157, v189
	v_sub_f32_e32 v188, v156, v188
	s_waitcnt lgkmcnt(2)
	v_sub_f32_e32 v187, v155, v187
	v_sub_f32_e32 v186, v154, v186
	v_sub_f32_e32 v185, v153, v185
	v_sub_f32_e32 v184, v152, v184
	s_waitcnt lgkmcnt(1)
	v_sub_f32_e32 v183, v151, v183
	v_sub_f32_e32 v182, v150, v182
	v_sub_f32_e32 v181, v149, v181
	v_sub_f32_e32 v180, v148, v180
	s_waitcnt lgkmcnt(0)
	v_sub_f32_e32 v179, v147, v179
	v_sub_f32_e32 v178, v146, v178
	v_sub_f32_e32 v177, v145, v177
	v_sub_f32_e32 v176, v144, v176
	ds_read_b128 v[98:101], v96 offset:9216
	ds_read_b128 v[136:139], v96 offset:13824
	ds_read_b128 v[140:143], v96 offset:9248
	v_max_f32_e32 v48, v1, v1
	v_max_f32_e32 v49, v0, v0
	v_max_f32_e32 v48, v49, v48
	v_max3_f32 v48, v48, v2, v3
	v_max3_f32 v48, v48, v4, v5
	v_max3_f32 v48, v48, v6, v7
	s_waitcnt lgkmcnt(2)
	v_mfma_f32_32x32x16_bf16 v[160:175], v[98:101], v[192:195], v[160:175]
	ds_read_b128 v[98:101], v96 offset:13856
	v_max3_f32 v48, v48, v8, v9
	v_max3_f32 v48, v48, v10, v11
	v_max3_f32 v48, v48, v12, v13
	v_max3_f32 v48, v48, v14, v15
	v_max3_f32 v48, v48, v16, v17
	v_max3_f32 v48, v48, v18, v19
	s_waitcnt lgkmcnt(2)
	v_mfma_f32_32x32x16_bf16 v[176:191], v[136:139], v[192:195], v[176:191]
	ds_read_b128 v[136:139], v96 offset:9280
	v_max3_f32 v48, v48, v20, v21
	v_max3_f32 v48, v48, v22, v23
	v_max3_f32 v48, v48, v24, v25
	v_max3_f32 v48, v48, v26, v27
	v_max3_f32 v48, v48, v28, v29
	v_max3_f32 v48, v48, v30, v31
	s_waitcnt lgkmcnt(2)
	v_mfma_f32_32x32x16_bf16 v[160:175], v[140:143], v[196:199], v[160:175]
	ds_read_b128 v[140:143], v96 offset:13888
	v_mov_b32_e32 v49, v48
	v_mov_b32_e32 v50, v48
	s_nop 1
	v_permlane32_swap_b32_e32 v49, v50
	v_cndmask_b32_e64 v49, v49, v50, s[38:39]
	v_max3_f32 v131, v97, v48, v49
	s_waitcnt lgkmcnt(2)
	v_mfma_f32_32x32x16_bf16 v[176:191], v[98:101], v[196:199], v[176:191]
	ds_read_b128 v[98:101], v96 offset:9312
	v_cmp_neq_f32_e32 vcc, s2, v131
	s_nop 1
	v_cndmask_b32_e32 v49, 0, v131, vcc
	v_sub_f32_e32 v48, v97, v49
	v_exp_f32_e32 v48, v48
	s_nop 0
	s_waitcnt lgkmcnt(2)
	v_mfma_f32_32x32x16_bf16 v[160:175], v[136:139], v[200:203], v[160:175]
	ds_read_b128 v[136:139], v96 offset:13920
	v_pk_mul_f32 v[46:47], v[46:47], v[48:49] op_sel_hi:[1,0]
	v_pk_mul_f32 v[44:45], v[44:45], v[48:49] op_sel_hi:[1,0]
	v_pk_mul_f32 v[42:43], v[42:43], v[48:49] op_sel_hi:[1,0]
	v_pk_mul_f32 v[40:41], v[40:41], v[48:49] op_sel_hi:[1,0]
	v_pk_mul_f32 v[38:39], v[38:39], v[48:49] op_sel_hi:[1,0]
	v_pk_mul_f32 v[36:37], v[36:37], v[48:49] op_sel_hi:[1,0]
	s_waitcnt lgkmcnt(2)
	v_mfma_f32_32x32x16_bf16 v[176:191], v[140:143], v[200:203], v[176:191]
	v_pk_mul_f32 v[34:35], v[34:35], v[48:49] op_sel_hi:[1,0]
	v_pk_mul_f32 v[32:33], v[32:33], v[48:49] op_sel_hi:[1,0]
	v_pk_mul_f32 v[94:95], v[94:95], v[48:49] op_sel_hi:[1,0]
	v_pk_mul_f32 v[92:93], v[92:93], v[48:49] op_sel_hi:[1,0]
	v_pk_mul_f32 v[90:91], v[90:91], v[48:49] op_sel_hi:[1,0]
	s_waitcnt lgkmcnt(1)
	v_mfma_f32_32x32x16_bf16 v[160:175], v[98:101], v[204:207], v[160:175]
	v_pk_mul_f32 v[88:89], v[88:89], v[48:49] op_sel_hi:[1,0]
	v_pk_mul_f32 v[86:87], v[86:87], v[48:49] op_sel_hi:[1,0]
	v_pk_mul_f32 v[84:85], v[84:85], v[48:49] op_sel_hi:[1,0]
	v_pk_mul_f32 v[82:83], v[82:83], v[48:49] op_sel_hi:[1,0]
	v_pk_mul_f32 v[80:81], v[80:81], v[48:49] op_sel_hi:[1,0]
	s_waitcnt lgkmcnt(0)
	v_mfma_f32_32x32x16_bf16 v[176:191], v[136:139], v[204:207], v[176:191]
	s_branch .LBB0_436
.Lfx3_slow:
	ds_read_b128 v[172:175], v244 offset:352
	ds_read_b128 v[168:171], v244 offset:320
	ds_read_b128 v[164:167], v244 offset:288
	ds_read_b128 v[160:163], v244 offset:256
	ds_read_b128 v[188:191], v244 offset:480
	ds_read_b128 v[184:187], v244 offset:448
	ds_read_b128 v[180:183], v244 offset:416
	ds_read_b128 v[176:179], v244 offset:384
	v_add_u32_e32 v96, v247, v243
	s_waitcnt lgkmcnt(7)
	v_sub_f32_e32 v175, v159, v175
	v_sub_f32_e32 v174, v158, v174
	v_sub_f32_e32 v173, v157, v173
	v_sub_f32_e32 v172, v156, v172
	s_waitcnt lgkmcnt(6)
	v_sub_f32_e32 v171, v155, v171
	v_sub_f32_e32 v170, v154, v170
	v_sub_f32_e32 v169, v153, v169
	v_sub_f32_e32 v168, v152, v168
	s_waitcnt lgkmcnt(5)
	v_sub_f32_e32 v167, v151, v167
	v_sub_f32_e32 v166, v150, v166
	v_sub_f32_e32 v165, v149, v165
	v_sub_f32_e32 v164, v148, v164
	s_waitcnt lgkmcnt(4)
	v_sub_f32_e32 v163, v147, v163
	v_sub_f32_e32 v162, v146, v162
	v_sub_f32_e32 v161, v145, v161
	v_sub_f32_e32 v160, v144, v160
	s_waitcnt lgkmcnt(3)
	v_sub_f32_e32 v191, v159, v191
	v_sub_f32_e32 v190, v158, v190
	v_sub_f32_e32 v189, v157, v189
	v_sub_f32_e32 v188, v156, v188
	s_waitcnt lgkmcnt(2)
	v_sub_f32_e32 v187, v155, v187
	v_sub_f32_e32 v186, v154, v186
	v_sub_f32_e32 v185, v153, v185
	v_sub_f32_e32 v184, v152, v184
	s_waitcnt lgkmcnt(1)
	v_sub_f32_e32 v183, v151, v183
	v_sub_f32_e32 v182, v150, v182
	v_sub_f32_e32 v181, v149, v181
	v_sub_f32_e32 v180, v148, v180
	s_waitcnt lgkmcnt(0)
	v_sub_f32_e32 v179, v147, v179
	v_sub_f32_e32 v178, v146, v178
	v_sub_f32_e32 v177, v145, v177
	v_sub_f32_e32 v176, v144, v176
	ds_read_b128 v[98:101], v96 offset:9216
	ds_read_b128 v[136:139], v96 offset:13824
	ds_read_b128 v[140:143], v96 offset:9248
	s_waitcnt lgkmcnt(2)
	v_mfma_f32_32x32x16_bf16 v[160:175], v[98:101], v[192:195], v[160:175]
	ds_read_b128 v[98:101], v96 offset:13856
	s_waitcnt lgkmcnt(2)
	v_mfma_f32_32x32x16_bf16 v[176:191], v[136:139], v[192:195], v[176:191]
	ds_read_b128 v[136:139], v96 offset:9280
	s_waitcnt lgkmcnt(2)
	v_mfma_f32_32x32x16_bf16 v[160:175], v[140:143], v[196:199], v[160:175]
	ds_read_b128 v[140:143], v96 offset:13888
	s_waitcnt lgkmcnt(2)
	v_mfma_f32_32x32x16_bf16 v[176:191], v[98:101], v[196:199], v[176:191]
	ds_read_b128 v[98:101], v96 offset:9312
	s_waitcnt lgkmcnt(2)
	v_mfma_f32_32x32x16_bf16 v[160:175], v[136:139], v[200:203], v[160:175]
	ds_read_b128 v[136:139], v96 offset:13920
	s_waitcnt lgkmcnt(2)
	v_mfma_f32_32x32x16_bf16 v[176:191], v[140:143], v[200:203], v[176:191]
	s_waitcnt lgkmcnt(1)
	v_mfma_f32_32x32x16_bf16 v[160:175], v[98:101], v[204:207], v[160:175]
	s_waitcnt lgkmcnt(0)
	v_mfma_f32_32x32x16_bf16 v[176:191], v[136:139], v[204:207], v[176:191]

.LBB0_446:
	s_cmp_gt_i32 s23, s21
	s_cbranch_scc1 .LBB0_448
	s_add_i32 s4, s23, 1
	s_cmp_gt_i32 s4, s21
	s_cbranch_scc1 .Lfx4_slow
	s_sub_i32 s4, s22, 64
	s_cmp_le_i32 s4, s31
	s_cbranch_scc0 .Lfx4_slow
	ds_read_b128 v[12:15], v244 offset:96
	ds_read_b128 v[8:11], v244 offset:64
	ds_read_b128 v[4:7], v244 offset:32
	ds_read_b128 v[0:3], v244
	ds_read_b128 v[28:31], v244 offset:224
	ds_read_b128 v[24:27], v244 offset:192
	ds_read_b128 v[20:23], v244 offset:160
	ds_read_b128 v[16:19], v244 offset:128
	v_add_u32_e32 v100, v247, v243
	s_waitcnt lgkmcnt(7)
	v_sub_f32_e32 v15, v159, v15
	v_sub_f32_e32 v14, v158, v14
	v_sub_f32_e32 v13, v157, v13
	v_sub_f32_e32 v12, v156, v12
	s_waitcnt lgkmcnt(6)
	v_sub_f32_e32 v11, v155, v11
	v_sub_f32_e32 v10, v154, v10
	v_sub_f32_e32 v9, v153, v9
	v_sub_f32_e32 v8, v152, v8
	s_waitcnt lgkmcnt(5)
	v_sub_f32_e32 v7, v151, v7
	v_sub_f32_e32 v6, v150, v6
	v_sub_f32_e32 v5, v149, v5
	v_sub_f32_e32 v4, v148, v4
	s_waitcnt lgkmcnt(4)
	v_sub_f32_e32 v3, v147, v3
	v_sub_f32_e32 v2, v146, v2
	v_sub_f32_e32 v1, v145, v1
	v_sub_f32_e32 v0, v144, v0
	s_waitcnt lgkmcnt(3)
	v_sub_f32_e32 v31, v159, v31
	v_sub_f32_e32 v30, v158, v30
	v_sub_f32_e32 v29, v157, v29
	v_sub_f32_e32 v28, v156, v28
	s_waitcnt lgkmcnt(2)
	v_sub_f32_e32 v27, v155, v27
	v_sub_f32_e32 v26, v154, v26
	v_sub_f32_e32 v25, v153, v25
	v_sub_f32_e32 v24, v152, v24
	s_waitcnt lgkmcnt(1)
	v_sub_f32_e32 v23, v151, v23
	v_sub_f32_e32 v22, v150, v22
	v_sub_f32_e32 v21, v149, v21
	v_sub_f32_e32 v20, v148, v20
	s_waitcnt lgkmcnt(0)
	v_sub_f32_e32 v19, v147, v19
	v_sub_f32_e32 v18, v146, v18
	v_sub_f32_e32 v17, v145, v17
	v_sub_f32_e32 v16, v144, v16
	ds_read_b128 v[64:67], v100
	ds_read_b128 v[136:139], v100 offset:4608
	ds_read_b128 v[140:143], v100 offset:32
	v_max_f32_e32 v96, v161, v161
	v_max_f32_e32 v97, v160, v160
	v_max_f32_e32 v96, v97, v96
	v_max3_f32 v96, v96, v162, v163
	v_max3_f32 v96, v96, v164, v165
	v_max3_f32 v96, v96, v166, v167
	s_waitcnt lgkmcnt(2)
	v_mfma_f32_32x32x16_bf16 v[0:15], v[64:67], v[192:195], v[0:15]
	ds_read_b128 v[64:67], v100 offset:4640
	v_max3_f32 v96, v96, v168, v169
	v_max3_f32 v96, v96, v170, v171
	v_max3_f32 v96, v96, v172, v173
	v_max3_f32 v96, v96, v174, v175
	v_max3_f32 v96, v96, v176, v177
	v_max3_f32 v96, v96, v178, v179
	s_waitcnt lgkmcnt(2)
	v_mfma_f32_32x32x16_bf16 v[16:31], v[136:139], v[192:195], v[16:31]
	ds_read_b128 v[136:139], v100 offset:64
	v_max3_f32 v96, v96, v180, v181
	v_max3_f32 v96, v96, v182, v183
	v_max3_f32 v96, v96, v184, v185
	v_max3_f32 v96, v96, v186, v187
	v_max3_f32 v96, v96, v188, v189
	v_max3_f32 v96, v96, v190, v191
	s_waitcnt lgkmcnt(2)
	v_mfma_f32_32x32x16_bf16 v[0:15], v[140:143], v[196:199], v[0:15]
	ds_read_b128 v[140:143], v100 offset:4672
	v_mov_b32_e32 v97, v96
	v_mov_b32_e32 v98, v96
	s_nop 1
	v_permlane32_swap_b32_e32 v97, v98
	v_cndmask_b32_e64 v97, v97, v98, s[38:39]
	v_max3_f32 v97, v131, v96, v97
	s_waitcnt lgkmcnt(2)
	v_mfma_f32_32x32x16_bf16 v[16:31], v[64:67], v[196:199], v[16:31]
	ds_read_b128 v[64:67], v100 offset:96
	v_cmp_neq_f32_e32 vcc, s2, v97
	s_nop 1
	v_cndmask_b32_e32 v98, 0, v97, vcc
	v_sub_f32_e32 v96, v131, v98
	v_exp_f32_e32 v96, v96
	s_nop 0
	s_waitcnt lgkmcnt(2)
	v_mfma_f32_32x32x16_bf16 v[0:15], v[136:139], v[200:203], v[0:15]
	ds_read_b128 v[136:139], v100 offset:4704
	v_pk_mul_f32 v[46:47], v[46:47], v[96:97] op_sel_hi:[1,0]
	v_pk_mul_f32 v[44:45], v[44:45], v[96:97] op_sel_hi:[1,0]
	v_pk_mul_f32 v[42:43], v[42:43], v[96:97] op_sel_hi:[1,0]
	v_pk_mul_f32 v[40:41], v[40:41], v[96:97] op_sel_hi:[1,0]
	v_pk_mul_f32 v[38:39], v[38:39], v[96:97] op_sel_hi:[1,0]
	v_pk_mul_f32 v[36:37], v[36:37], v[96:97] op_sel_hi:[1,0]
	s_waitcnt lgkmcnt(2)
	v_mfma_f32_32x32x16_bf16 v[16:31], v[140:143], v[200:203], v[16:31]
	v_pk_mul_f32 v[34:35], v[34:35], v[96:97] op_sel_hi:[1,0]
	v_pk_mul_f32 v[32:33], v[32:33], v[96:97] op_sel_hi:[1,0]
	v_pk_mul_f32 v[62:63], v[62:63], v[96:97] op_sel_hi:[1,0]
	v_pk_mul_f32 v[60:61], v[60:61], v[96:97] op_sel_hi:[1,0]
	v_pk_mul_f32 v[58:59], v[58:59], v[96:97] op_sel_hi:[1,0]
	s_waitcnt lgkmcnt(1)
	v_mfma_f32_32x32x16_bf16 v[0:15], v[64:67], v[204:207], v[0:15]
	v_pk_mul_f32 v[56:57], v[56:57], v[96:97] op_sel_hi:[1,0]
	v_pk_mul_f32 v[54:55], v[54:55], v[96:97] op_sel_hi:[1,0]
	v_pk_mul_f32 v[52:53], v[52:53], v[96:97] op_sel_hi:[1,0]
	v_pk_mul_f32 v[50:51], v[50:51], v[96:97] op_sel_hi:[1,0]
	v_pk_mul_f32 v[48:49], v[48:49], v[96:97] op_sel_hi:[1,0]
	s_waitcnt lgkmcnt(0)
	v_mfma_f32_32x32x16_bf16 v[16:31], v[136:139], v[204:207], v[16:31]
	s_branch .LBB0_455
.Lfx4_slow:
	ds_read_b128 v[12:15], v244 offset:96
	ds_read_b128 v[8:11], v244 offset:64
	ds_read_b128 v[4:7], v244 offset:32
	ds_read_b128 v[0:3], v244
	ds_read_b128 v[28:31], v244 offset:224
	ds_read_b128 v[24:27], v244 offset:192
	ds_read_b128 v[20:23], v244 offset:160
	ds_read_b128 v[16:19], v244 offset:128
	v_add_u32_e32 v100, v247, v243
	s_waitcnt lgkmcnt(7)
	v_sub_f32_e32 v15, v159, v15
	v_sub_f32_e32 v14, v158, v14
	v_sub_f32_e32 v13, v157, v13
	v_sub_f32_e32 v12, v156, v12
	s_waitcnt lgkmcnt(6)
	v_sub_f32_e32 v11, v155, v11
	v_sub_f32_e32 v10, v154, v10
	v_sub_f32_e32 v9, v153, v9
	v_sub_f32_e32 v8, v152, v8
	s_waitcnt lgkmcnt(5)
	v_sub_f32_e32 v7, v151, v7
	v_sub_f32_e32 v6, v150, v6
	v_sub_f32_e32 v5, v149, v5
	v_sub_f32_e32 v4, v148, v4
	s_waitcnt lgkmcnt(4)
	v_sub_f32_e32 v3, v147, v3
	v_sub_f32_e32 v2, v146, v2
	v_sub_f32_e32 v1, v145, v1
	v_sub_f32_e32 v0, v144, v0
	s_waitcnt lgkmcnt(3)
	v_sub_f32_e32 v31, v159, v31
	v_sub_f32_e32 v30, v158, v30
	v_sub_f32_e32 v29, v157, v29
	v_sub_f32_e32 v28, v156, v28
	s_waitcnt lgkmcnt(2)
	v_sub_f32_e32 v27, v155, v27
	v_sub_f32_e32 v26, v154, v26
	v_sub_f32_e32 v25, v153, v25
	v_sub_f32_e32 v24, v152, v24
	s_waitcnt lgkmcnt(1)
	v_sub_f32_e32 v23, v151, v23
	v_sub_f32_e32 v22, v150, v22
	v_sub_f32_e32 v21, v149, v21
	v_sub_f32_e32 v20, v148, v20
	s_waitcnt lgkmcnt(0)
	v_sub_f32_e32 v19, v147, v19
	v_sub_f32_e32 v18, v146, v18
	v_sub_f32_e32 v17, v145, v17
	v_sub_f32_e32 v16, v144, v16
	ds_read_b128 v[96:99], v100
	ds_read_b128 v[136:139], v100 offset:4608
	ds_read_b128 v[140:143], v100 offset:32
	s_waitcnt lgkmcnt(2)
	v_mfma_f32_32x32x16_bf16 v[0:15], v[96:99], v[192:195], v[0:15]
	ds_read_b128 v[96:99], v100 offset:4640
	s_waitcnt lgkmcnt(2)
	v_mfma_f32_32x32x16_bf16 v[16:31], v[136:139], v[192:195], v[16:31]
	ds_read_b128 v[136:139], v100 offset:64
	s_waitcnt lgkmcnt(2)
	v_mfma_f32_32x32x16_bf16 v[0:15], v[140:143], v[196:199], v[0:15]
	ds_read_b128 v[140:143], v100 offset:4672
	s_waitcnt lgkmcnt(2)
	v_mfma_f32_32x32x16_bf16 v[16:31], v[96:99], v[196:199], v[16:31]
	ds_read_b128 v[96:99], v100 offset:96
	s_waitcnt lgkmcnt(2)
	v_mfma_f32_32x32x16_bf16 v[0:15], v[136:139], v[200:203], v[0:15]
	ds_read_b128 v[136:139], v100 offset:4704
	s_waitcnt lgkmcnt(2)
	v_mfma_f32_32x32x16_bf16 v[16:31], v[140:143], v[200:203], v[16:31]
	s_waitcnt lgkmcnt(1)
	v_mfma_f32_32x32x16_bf16 v[0:15], v[96:99], v[204:207], v[0:15]
	s_waitcnt lgkmcnt(0)
	v_mfma_f32_32x32x16_bf16 v[16:31], v[136:139], v[204:207], v[16:31]
